# sub-LN butterfly: xor-1/2 exchanges via DPP quad_perm and xor-4/8 via row_half_mirror/row_mirror fused into v_add_f32_dpp (bit-identical), only the xor-16 round stays a batched ds_bpermute; stacked on
# baseline (speedup 1.0000x reference)
; template <int MODE> ...
;     ...
;         __syncthreads();
;         if (mapi == 0) {
;             float ss[16];
; #pragma unroll
;             for (int r = 0; r < 16; ++r) { float s = 0.f;
; #pragma unroll
;                 for (int c = 0; c < NC; ++c) { const float y = O[c][r] * il[r] - lam * xc[(c * 16 + r) * 256]; O[c][r] = y; s += y * y; }
;                 ss[r] = s; }
;     ...
;             float gsub[NC];
; #pragma unroll
;             for (int c = 0; c < NC; ++c) gsub[c] = subg[32 * c + r32] * subfac;
.LBB0_307:
	s_cmpk_gt_u32 s76, 0xff
	s_waitcnt lgkmcnt(0)
	s_barrier
	s_cbranch_scc1 .LBB0_309
	v_lshlrev_b32_e32 v105, 2, v178
	global_load_dword v106, v105, s[46:47]
	global_load_dword v107, v105, s[46:47] offset:128
	global_load_dword v108, v105, s[46:47] offset:256
	global_load_dword v109, v105, s[46:47] offset:384
	ds_read2st64_b32 v[82:83], v0 offset1:4
	ds_read2st64_b32 v[84:85], v0 offset0:64 offset1:68
	ds_read2st64_b32 v[86:87], v0 offset0:128 offset1:132
	ds_read2st64_b32 v[88:89], v0 offset0:192 offset1:196
	s_lshl_b32 s1, s1, 1
	s_waitcnt lgkmcnt(3)
	v_mul_f32_e32 v82, s17, v82
	v_fma_f32 v96, v50, v78, -v82
	s_waitcnt lgkmcnt(2)
	v_mul_f32_e32 v50, s17, v84
	v_fma_f32 v97, v34, v78, -v50
	s_waitcnt lgkmcnt(1)
	v_mul_f32_e32 v34, s17, v86
	v_fma_f32 v98, v18, v78, -v34
	s_waitcnt lgkmcnt(0)
	v_mul_f32_e32 v18, s17, v88
	v_fma_f32 v99, v2, v78, -v18
	v_mul_f32_e32 v18, s17, v87
	v_mul_f32_e32 v2, s17, v83
	v_fma_f32 v92, v19, v79, -v18
	v_mul_f32_e32 v18, s17, v89
	v_fma_f32 v94, v51, v79, -v2
	v_mul_f32_e32 v2, s17, v85
	v_fma_f32 v93, v3, v79, -v18
	ds_read2st64_b32 v[18:19], v0 offset0:8 offset1:12
	ds_read2st64_b32 v[50:51], v0 offset0:136 offset1:140
	v_fma_f32 v91, v35, v79, -v2
	ds_read2st64_b32 v[78:79], v0 offset0:200 offset1:204
	ds_read2st64_b32 v[34:35], v0 offset0:72 offset1:76
	s_waitcnt lgkmcnt(3)
	v_mul_f32_e32 v3, s17, v18
	s_waitcnt lgkmcnt(2)
	v_mul_f32_e32 v18, s17, v50
	v_fma_f32 v90, v20, v80, -v18
	s_waitcnt lgkmcnt(1)
	v_mul_f32_e32 v18, s17, v78
	v_fma_f32 v95, v4, v80, -v18
	v_mul_f32_e32 v4, s17, v19
	v_fma_f32 v87, v53, v81, -v4
	s_waitcnt lgkmcnt(0)
	v_mul_f32_e32 v4, s17, v35
	v_fma_f32 v83, v37, v81, -v4
	v_mul_f32_e32 v4, s17, v51
	v_fma_f32 v84, v21, v81, -v4
	v_mul_f32_e32 v4, s17, v79
	v_fma_f32 v85, v5, v81, -v4
	ds_read2st64_b32 v[4:5], v0 offset0:16 offset1:20
	ds_read2st64_b32 v[18:19], v0 offset0:80 offset1:84
	ds_read2st64_b32 v[20:21], v0 offset0:144 offset1:148
	v_fma_f32 v88, v52, v80, -v3
	v_mul_f32_e32 v3, s17, v34
	ds_read2st64_b32 v[34:35], v0 offset0:208 offset1:212
	s_waitcnt lgkmcnt(3)
	v_mul_f32_e32 v4, s17, v4
	v_fma_f32 v89, v36, v80, -v3
	v_fma_f32 v80, v54, v74, -v4
	s_waitcnt lgkmcnt(2)
	v_mul_f32_e32 v4, s17, v18
	v_fma_f32 v81, v38, v74, -v4
	s_waitcnt lgkmcnt(1)
	v_mul_f32_e32 v4, s17, v20
	v_fma_f32 v82, v22, v74, -v4
	s_waitcnt lgkmcnt(0)
	v_mul_f32_e32 v4, s17, v34
	v_fma_f32 v86, v6, v74, -v4
	v_mul_f32_e32 v4, s17, v5
	v_fma_f32 v79, v55, v75, -v4
	v_mul_f32_e32 v4, s17, v19
	v_fma_f32 v74, v39, v75, -v4
	v_mul_f32_e32 v4, s17, v21
	v_fma_f32 v78, v23, v75, -v4
	v_mul_f32_e32 v4, s17, v35
	v_fma_f32 v75, v7, v75, -v4
	ds_read2st64_b32 v[4:5], v0 offset0:24 offset1:28
	ds_read2st64_b32 v[6:7], v0 offset0:88 offset1:92
	ds_read2st64_b32 v[18:19], v0 offset0:152 offset1:156
	ds_read2st64_b32 v[20:21], v0 offset0:216 offset1:220
	v_mul_f32_e32 v100, v97, v97
	s_waitcnt lgkmcnt(3)
	v_mul_f32_e32 v4, s17, v4
	v_fma_f32 v54, v56, v76, -v4
	s_waitcnt lgkmcnt(2)
	v_mul_f32_e32 v4, s17, v6
	v_fma_f32 v55, v40, v76, -v4
	s_waitcnt lgkmcnt(1)
	v_mul_f32_e32 v4, s17, v18
	v_fma_f32 v56, v24, v76, -v4
	s_waitcnt lgkmcnt(0)
	v_mul_f32_e32 v4, s17, v20
	v_fma_f32 v76, v8, v76, -v4
	v_mul_f32_e32 v4, s17, v5
	v_fma_f32 v53, v57, v77, -v4
	v_mul_f32_e32 v4, s17, v7
	v_fma_f32 v50, v41, v77, -v4
	v_mul_f32_e32 v4, s17, v19
	v_fma_f32 v51, v25, v77, -v4
	v_mul_f32_e32 v4, s17, v21
	v_fma_f32 v52, v9, v77, -v4
	ds_read2st64_b32 v[4:5], v0 offset0:32 offset1:36
	ds_read2st64_b32 v[6:7], v0 offset0:96 offset1:100
	ds_read2st64_b32 v[8:9], v0 offset0:160 offset1:164
	ds_read2st64_b32 v[18:19], v0 offset0:224 offset1:228
	v_fmac_f32_e32 v100, v96, v96
	s_waitcnt lgkmcnt(3)
	v_mul_f32_e32 v4, s17, v4
	v_fma_f32 v39, v58, v70, -v4
	s_waitcnt lgkmcnt(2)
	v_mul_f32_e32 v4, s17, v6
	v_fma_f32 v40, v42, v70, -v4
	s_waitcnt lgkmcnt(1)
	v_mul_f32_e32 v4, s17, v8
	v_fma_f32 v41, v26, v70, -v4
	s_waitcnt lgkmcnt(0)
	v_mul_f32_e32 v4, s17, v18
	v_fma_f32 v42, v10, v70, -v4
	v_mul_f32_e32 v4, s17, v5
	v_fma_f32 v37, v59, v71, -v4
	v_mul_f32_e32 v4, s17, v7
	v_fma_f32 v34, v43, v71, -v4
	v_mul_f32_e32 v4, s17, v9
	v_fma_f32 v35, v27, v71, -v4
	v_mul_f32_e32 v4, s17, v19
	v_fma_f32 v36, v11, v71, -v4
	ds_read2st64_b32 v[4:5], v0 offset0:40 offset1:44
	ds_read2st64_b32 v[6:7], v0 offset0:104 offset1:108
	ds_read2st64_b32 v[8:9], v0 offset0:168 offset1:172
	ds_read2st64_b32 v[10:11], v0 offset0:232 offset1:236
	v_fmac_f32_e32 v100, v98, v98
	s_waitcnt lgkmcnt(3)
	v_mul_f32_e32 v4, s17, v4
	v_fma_f32 v26, v60, v72, -v4
	s_waitcnt lgkmcnt(2)
	v_mul_f32_e32 v4, s17, v6
	v_fma_f32 v27, v44, v72, -v4
	s_waitcnt lgkmcnt(1)
	v_mul_f32_e32 v4, s17, v8
	v_fma_f32 v28, v28, v72, -v4
	s_waitcnt lgkmcnt(0)
	v_mul_f32_e32 v4, s17, v10
	v_fma_f32 v38, v12, v72, -v4
	v_mul_f32_e32 v4, s17, v5
	v_fma_f32 v25, v61, v73, -v4
	v_mul_f32_e32 v4, s17, v7
	v_fma_f32 v21, v45, v73, -v4
	v_mul_f32_e32 v4, s17, v9
	v_fma_f32 v22, v29, v73, -v4
	v_mul_f32_e32 v4, s17, v11
	v_fma_f32 v23, v13, v73, -v4
	ds_read2st64_b32 v[4:5], v0 offset0:48 offset1:52
	ds_read2st64_b32 v[6:7], v0 offset0:112 offset1:116
	ds_read2st64_b32 v[8:9], v0 offset0:176 offset1:180
	ds_read2st64_b32 v[12:13], v0 offset0:240 offset1:244
	ds_read2st64_b32 v[44:45], v0 offset0:184 offset1:188
	s_waitcnt lgkmcnt(4)
	v_mul_f32_e32 v4, s17, v4
	v_fma_f32 v18, v62, v66, -v4
	s_waitcnt lgkmcnt(3)
	v_mul_f32_e32 v4, s17, v6
	v_fma_f32 v19, v46, v66, -v4
	s_waitcnt lgkmcnt(2)
	v_mul_f32_e32 v4, s17, v8
	v_fma_f32 v20, v30, v66, -v4
	s_waitcnt lgkmcnt(1)
; template <int MODE> ...
;     ...
;             float ss[16];
; #pragma unroll
;             for (int r = 0; r < 16; ++r) { float s = 0.f;
; #pragma unroll
;                 for (int c = 0; c < NC; ++c) { const float y = O[c][r] * il[r] - lam * xc[(c * 16 + r) * 256]; O[c][r] = y; s += y * y; }
;                 ss[r] = s; }
; #pragma unroll
;             for (int o = 1; o < 32; o <<= 1)
; #pragma unroll
;                 for (int r = 0; r < 16; ++r) ss[r] += __shfl_xor(ss[r], o);
	v_mul_f32_e32 v4, s17, v12
	v_fma_f32 v24, v14, v66, -v4
	v_mul_f32_e32 v4, s17, v5
	v_fma_f32 v14, v63, v67, -v4
	v_mul_f32_e32 v4, s17, v7
	v_fma_f32 v11, v47, v67, -v4
	v_mul_f32_e32 v4, s17, v9
	v_fma_f32 v12, v31, v67, -v4
	v_mul_f32_e32 v4, s17, v13
	v_fma_f32 v13, v15, v67, -v4
	ds_read2st64_b32 v[4:5], v0 offset0:56 offset1:60
	ds_read2st64_b32 v[30:31], v0 offset0:120 offset1:124
	ds_read2st64_b32 v[46:47], v0 offset0:248 offset1:252
	v_fmac_f32_e32 v100, v99, v99
	v_mul_f32_e32 v2, v91, v91
	s_waitcnt lgkmcnt(2)
	v_mul_f32_e32 v4, s17, v4
	v_fma_f32 v8, v64, v68, -v4
	s_waitcnt lgkmcnt(1)
	v_mul_f32_e32 v4, s17, v30
	v_fma_f32 v9, v48, v68, -v4
	v_mul_f32_e32 v30, v9, v9
	v_mul_f32_e32 v4, s17, v44
	v_fmac_f32_e32 v30, v8, v8
	v_fma_f32 v10, v32, v68, -v4
	s_waitcnt lgkmcnt(0)
	v_mul_f32_e32 v0, s17, v46
	v_fmac_f32_e32 v30, v10, v10
	v_fma_f32 v15, v16, v68, -v0
	v_mul_f32_e32 v0, s17, v5
	v_fmac_f32_e32 v30, v15, v15
	v_fma_f32 v7, v65, v69, -v0
	v_mul_f32_e32 v0, s17, v31
	v_fma_f32 v4, v49, v69, -v0
	s_nop 1
	v_mov_b32_dpp v49, v30 quad_perm:[1,0,3,2] row_mask:0xf bank_mask:0xf
	v_mul_f32_e32 v0, v4, v4
	v_mul_f32_e32 v5, s17, v45
	v_fmac_f32_e32 v0, v7, v7
	v_fma_f32 v5, v33, v69, -v5
	v_mul_f32_e32 v6, s17, v47
	v_fmac_f32_e32 v0, v5, v5
	v_fma_f32 v6, v17, v69, -v6
	v_fmac_f32_e32 v0, v6, v6
	s_nop 1
	v_mov_b32_dpp v16, v100 quad_perm:[1,0,3,2] row_mask:0xf bank_mask:0xf
	s_waitcnt lgkmcnt(1)
	v_add_f32_e32 v30, v30, v49
	s_nop 1
	v_mov_b32_dpp v49, v0 quad_perm:[1,0,3,2] row_mask:0xf bank_mask:0xf
	v_fmac_f32_e32 v2, v94, v94
	v_fmac_f32_e32 v2, v92, v92
	v_fmac_f32_e32 v2, v93, v93
	s_waitcnt lgkmcnt(1)
	v_add_f32_e32 v16, v100, v16
	s_nop 1
	v_mov_b32_dpp v17, v2 quad_perm:[1,0,3,2] row_mask:0xf bank_mask:0xf
	v_mul_f32_e32 v3, v89, v89
	s_waitcnt lgkmcnt(1)
	v_add_f32_e32 v0, v0, v49
	s_nop 1
	v_mov_b32_dpp v49, v16 quad_perm:[2,3,0,1] row_mask:0xf bank_mask:0xf
	v_fmac_f32_e32 v3, v88, v88
	v_fmac_f32_e32 v3, v90, v90
	v_fmac_f32_e32 v3, v95, v95
	s_waitcnt lgkmcnt(1)
	v_add_f32_e32 v2, v2, v17
	s_nop 1
	v_mov_b32_dpp v17, v3 quad_perm:[1,0,3,2] row_mask:0xf bank_mask:0xf
	v_mul_f32_e32 v101, v83, v83
	s_waitcnt lgkmcnt(1)
	v_add_f32_e32 v16, v16, v49
	s_nop 1
	v_mov_b32_dpp v49, v2 quad_perm:[2,3,0,1] row_mask:0xf bank_mask:0xf
	v_fmac_f32_e32 v101, v87, v87
	v_fmac_f32_e32 v101, v84, v84
	v_fmac_f32_e32 v101, v85, v85
	s_waitcnt lgkmcnt(1)
	v_add_f32_e32 v3, v3, v17
	s_nop 1
	v_mov_b32_dpp v17, v101 quad_perm:[1,0,3,2] row_mask:0xf bank_mask:0xf
	v_mul_f32_e32 v102, v81, v81
	s_waitcnt lgkmcnt(1)
	v_add_f32_e32 v2, v2, v49
	s_nop 1
	v_mov_b32_dpp v49, v3 quad_perm:[2,3,0,1] row_mask:0xf bank_mask:0xf
	v_fmac_f32_e32 v102, v80, v80
	v_fmac_f32_e32 v102, v82, v82
	v_fmac_f32_e32 v102, v86, v86
	s_waitcnt lgkmcnt(1)
	v_add_f32_e32 v17, v101, v17
	s_nop 1
	v_mov_b32_dpp v31, v102 quad_perm:[1,0,3,2] row_mask:0xf bank_mask:0xf
	v_mul_f32_e32 v103, v74, v74
	s_waitcnt lgkmcnt(1)
	v_add_f32_e32 v3, v3, v49
	s_nop 1
	v_mov_b32_dpp v49, v17 quad_perm:[2,3,0,1] row_mask:0xf bank_mask:0xf
	v_fmac_f32_e32 v103, v79, v79
	v_fmac_f32_e32 v103, v78, v78
	v_fmac_f32_e32 v103, v75, v75
	s_waitcnt lgkmcnt(1)
	v_add_f32_e32 v31, v102, v31
	s_nop 1
	v_mov_b32_dpp v32, v103 quad_perm:[1,0,3,2] row_mask:0xf bank_mask:0xf
	v_mul_f32_e32 v104, v55, v55
	s_waitcnt lgkmcnt(1)
	v_add_f32_e32 v17, v17, v49
	s_nop 1
	v_mov_b32_dpp v49, v31 quad_perm:[2,3,0,1] row_mask:0xf bank_mask:0xf
	v_fmac_f32_e32 v104, v54, v54
	v_fmac_f32_e32 v104, v56, v56
	v_fmac_f32_e32 v104, v76, v76
	s_waitcnt lgkmcnt(1)
	v_add_f32_e32 v32, v103, v32
	s_nop 1
	v_mov_b32_dpp v33, v104 quad_perm:[1,0,3,2] row_mask:0xf bank_mask:0xf
	v_mul_f32_e32 v57, v50, v50
	s_waitcnt lgkmcnt(1)
	v_add_f32_e32 v31, v31, v49
	s_nop 1
	v_mov_b32_dpp v49, v32 quad_perm:[2,3,0,1] row_mask:0xf bank_mask:0xf
	v_fmac_f32_e32 v57, v53, v53
	v_fmac_f32_e32 v57, v51, v51
	v_fmac_f32_e32 v57, v52, v52
	s_waitcnt lgkmcnt(1)
	v_add_f32_e32 v33, v104, v33
	s_nop 1
	v_mov_b32_dpp v44, v57 quad_perm:[1,0,3,2] row_mask:0xf bank_mask:0xf
	v_mul_f32_e32 v58, v40, v40
	s_waitcnt lgkmcnt(1)
	v_add_f32_e32 v32, v32, v49
	s_nop 1
	v_mov_b32_dpp v49, v33 quad_perm:[2,3,0,1] row_mask:0xf bank_mask:0xf
	v_fmac_f32_e32 v58, v39, v39
	v_fmac_f32_e32 v58, v41, v41
	v_fmac_f32_e32 v58, v42, v42
	s_waitcnt lgkmcnt(1)
	v_add_f32_e32 v44, v57, v44
	s_nop 1
	v_mov_b32_dpp v45, v58 quad_perm:[1,0,3,2] row_mask:0xf bank_mask:0xf
	v_mul_f32_e32 v43, v34, v34
	s_waitcnt lgkmcnt(1)
	v_add_f32_e32 v33, v33, v49
	s_nop 1
	v_mov_b32_dpp v49, v44 quad_perm:[2,3,0,1] row_mask:0xf bank_mask:0xf
	v_fmac_f32_e32 v43, v37, v37
	v_fmac_f32_e32 v43, v35, v35
	v_fmac_f32_e32 v43, v36, v36
	s_waitcnt lgkmcnt(1)
	v_add_f32_e32 v45, v58, v45
	s_nop 1
	v_mov_b32_dpp v46, v43 quad_perm:[1,0,3,2] row_mask:0xf bank_mask:0xf
	v_mul_f32_e32 v59, v27, v27
	s_waitcnt lgkmcnt(1)
	v_add_f32_e32 v44, v44, v49
	s_nop 1
	v_mov_b32_dpp v49, v45 quad_perm:[2,3,0,1] row_mask:0xf bank_mask:0xf
	v_fmac_f32_e32 v59, v26, v26
	v_fmac_f32_e32 v59, v28, v28
	v_fmac_f32_e32 v59, v38, v38
	s_waitcnt lgkmcnt(1)
	v_add_f32_e32 v43, v43, v46
	s_nop 1
	v_mov_b32_dpp v46, v59 quad_perm:[1,0,3,2] row_mask:0xf bank_mask:0xf
	v_mul_f32_e32 v60, v21, v21
	s_waitcnt lgkmcnt(1)
	v_add_f32_e32 v45, v45, v49
	s_nop 1
	v_mov_b32_dpp v49, v43 quad_perm:[2,3,0,1] row_mask:0xf bank_mask:0xf
	v_fmac_f32_e32 v60, v25, v25
	v_fmac_f32_e32 v60, v22, v22
	v_fmac_f32_e32 v60, v23, v23
	s_waitcnt lgkmcnt(1)
	v_add_f32_e32 v46, v59, v46
	s_nop 1
	v_mov_b32_dpp v47, v60 quad_perm:[1,0,3,2] row_mask:0xf bank_mask:0xf
	v_mul_f32_e32 v29, v19, v19
	s_waitcnt lgkmcnt(1)
; template <int MODE> ...
;     ...
; #pragma unroll
;             for (int o = 1; o < 32; o <<= 1)
; #pragma unroll
;                 for (int r = 0; r < 16; ++r) ss[r] += __shfl_xor(ss[r], o);
;             float gsub[NC];
; #pragma unroll
;             for (int c = 0; c < NC; ++c) gsub[c] = subg[32 * c + r32] * subfac;
	v_add_f32_e32 v43, v43, v49
	s_nop 1
	v_mov_b32_dpp v49, v46 quad_perm:[2,3,0,1] row_mask:0xf bank_mask:0xf
	v_fmac_f32_e32 v29, v18, v18
	v_fmac_f32_e32 v29, v20, v20
	v_fmac_f32_e32 v29, v24, v24
	s_waitcnt lgkmcnt(1)
	v_add_f32_e32 v47, v60, v47
	s_nop 1
	v_mov_b32_dpp v48, v29 quad_perm:[1,0,3,2] row_mask:0xf bank_mask:0xf
	v_mul_f32_e32 v61, v11, v11
	s_waitcnt lgkmcnt(1)
	v_add_f32_e32 v46, v46, v49
	s_nop 1
	v_mov_b32_dpp v49, v47 quad_perm:[2,3,0,1] row_mask:0xf bank_mask:0xf
	v_fmac_f32_e32 v61, v14, v14
	v_fmac_f32_e32 v61, v12, v12
	v_fmac_f32_e32 v61, v13, v13
	s_waitcnt lgkmcnt(1)
	v_add_f32_e32 v29, v29, v48
	s_nop 1
	v_mov_b32_dpp v48, v61 quad_perm:[1,0,3,2] row_mask:0xf bank_mask:0xf
	s_waitcnt lgkmcnt(1)
	v_add_f32_e32 v47, v47, v49
	s_nop 1
	v_mov_b32_dpp v49, v29 quad_perm:[2,3,0,1] row_mask:0xf bank_mask:0xf
	s_add_u32 s4, s78, s1
	s_addc_u32 s5, s79, 0
	s_waitcnt lgkmcnt(1)
	v_add_f32_e32 v48, v61, v48
	s_movk_i32 s1, 0x2000
	s_waitcnt lgkmcnt(0)
	v_add_f32_e32 v29, v29, v49
	v_add_f32_dpp v48, v48, v48 quad_perm:[2,3,0,1] row_mask:0xf bank_mask:0xf
	v_add_f32_dpp v30, v30, v30 quad_perm:[2,3,0,1] row_mask:0xf bank_mask:0xf
	v_add_f32_dpp v0, v0, v0 quad_perm:[2,3,0,1] row_mask:0xf bank_mask:0xf
	v_add_f32_dpp v16, v16, v16 row_half_mirror row_mask:0xf bank_mask:0xf
	v_add_f32_dpp v2, v2, v2 row_half_mirror row_mask:0xf bank_mask:0xf
	v_add_f32_dpp v3, v3, v3 row_half_mirror row_mask:0xf bank_mask:0xf
	v_add_f32_dpp v17, v17, v17 row_half_mirror row_mask:0xf bank_mask:0xf
	v_add_f32_dpp v31, v31, v31 row_half_mirror row_mask:0xf bank_mask:0xf
	v_add_f32_dpp v32, v32, v32 row_half_mirror row_mask:0xf bank_mask:0xf
	v_add_f32_dpp v33, v33, v33 row_half_mirror row_mask:0xf bank_mask:0xf
	v_add_f32_dpp v44, v44, v44 row_half_mirror row_mask:0xf bank_mask:0xf
	v_add_f32_dpp v45, v45, v45 row_half_mirror row_mask:0xf bank_mask:0xf
	v_add_f32_dpp v43, v43, v43 row_half_mirror row_mask:0xf bank_mask:0xf
	v_add_f32_dpp v46, v46, v46 row_half_mirror row_mask:0xf bank_mask:0xf
	v_add_f32_dpp v47, v47, v47 row_half_mirror row_mask:0xf bank_mask:0xf
	v_add_f32_dpp v29, v29, v29 row_half_mirror row_mask:0xf bank_mask:0xf
	v_add_f32_dpp v48, v48, v48 row_half_mirror row_mask:0xf bank_mask:0xf
	v_add_f32_dpp v30, v30, v30 row_half_mirror row_mask:0xf bank_mask:0xf
	v_add_f32_dpp v0, v0, v0 row_half_mirror row_mask:0xf bank_mask:0xf
	v_add_f32_dpp v16, v16, v16 row_mirror row_mask:0xf bank_mask:0xf
	v_add_f32_dpp v49, v2, v2 row_mirror row_mask:0xf bank_mask:0xf
	v_add_f32_dpp v3, v3, v3 row_mirror row_mask:0xf bank_mask:0xf
	v_add_f32_dpp v17, v17, v17 row_mirror row_mask:0xf bank_mask:0xf
	v_add_f32_dpp v31, v31, v31 row_mirror row_mask:0xf bank_mask:0xf
	v_add_f32_dpp v32, v32, v32 row_mirror row_mask:0xf bank_mask:0xf
	v_add_f32_dpp v33, v33, v33 row_mirror row_mask:0xf bank_mask:0xf
	v_add_f32_dpp v44, v44, v44 row_mirror row_mask:0xf bank_mask:0xf
	v_add_f32_dpp v45, v45, v45 row_mirror row_mask:0xf bank_mask:0xf
	v_add_f32_dpp v43, v43, v43 row_mirror row_mask:0xf bank_mask:0xf
	v_add_f32_dpp v62, v46, v46 row_mirror row_mask:0xf bank_mask:0xf
	v_add_f32_dpp v63, v47, v47 row_mirror row_mask:0xf bank_mask:0xf
	v_add_f32_dpp v29, v29, v29 row_mirror row_mask:0xf bank_mask:0xf
	v_add_f32_dpp v64, v48, v48 row_mirror row_mask:0xf bank_mask:0xf
	v_add_f32_dpp v30, v30, v30 row_mirror row_mask:0xf bank_mask:0xf
	v_add_f32_dpp v0, v0, v0 row_mirror row_mask:0xf bank_mask:0xf
	ds_bpermute_b32 v110, v195, v16
	ds_bpermute_b32 v111, v195, v49
	ds_bpermute_b32 v112, v195, v3
	ds_bpermute_b32 v113, v195, v17
	ds_bpermute_b32 v114, v195, v31
	ds_bpermute_b32 v115, v195, v32
	ds_bpermute_b32 v116, v195, v33
	ds_bpermute_b32 v117, v195, v44
	ds_bpermute_b32 v118, v195, v45
	ds_bpermute_b32 v119, v195, v43
	ds_bpermute_b32 v120, v195, v62
	ds_bpermute_b32 v121, v195, v63
	ds_bpermute_b32 v122, v195, v29
	ds_bpermute_b32 v123, v195, v64
	ds_bpermute_b32 v124, v195, v30
	s_waitcnt lgkmcnt(7)
	v_add_f32_e32 v2, v16, v110
	v_add_f32_e32 v61, v49, v111
	v_add_f32_e32 v60, v3, v112
	v_add_f32_e32 v59, v17, v113
	v_add_f32_e32 v58, v31, v114
	v_add_f32_e32 v57, v32, v115
	v_add_f32_e32 v49, v33, v116
	v_add_f32_e32 v48, v44, v117
	ds_bpermute_b32 v125, v195, v0
	s_waitcnt lgkmcnt(0)
	v_add_f32_e32 v47, v45, v118
	v_add_f32_e32 v46, v43, v119
	v_add_f32_e32 v44, v62, v120
	v_add_f32_e32 v43, v63, v121
	v_add_f32_e32 v33, v29, v122
	v_add_f32_e32 v29, v64, v123
	v_add_f32_e32 v17, v30, v124
	v_add_f32_e32 v16, v0, v125
	s_waitcnt vmcnt(0)
; __device__ __forceinline__ unsigned pk2(float lo, float hi) { return pg8::cvt_pk_bf16(lo, hi); }
; __device__ __forceinline__ int crow(int r, int hi) { return (r & 3) + 8 * (r >> 2) + 4 * hi; }
; template <int MODE> ...
;     ...
; #pragma unroll
;             for (int r = 0; r < 16; ++r) { const float inv = 1.0f / sqrtf(ss[r] * (1.f / 128.f) + 1e-5f); bf16* yp = Y + (tok0 + wq0 + crow(r, hi)) * 1536 + ycol + r32;
; #pragma unroll
;                 for (int c = 0; c < NC; ++c) yp[32 * c] = (bf16)(pk2(O[c][r] * inv * gsub[c], 0.f) & 0xffffu); }
	v_mul_f32_e32 v32, v205, v106
	v_mul_f32_e32 v30, v205, v107
	v_mul_f32_e32 v31, v205, v108
	v_or_b32_e32 v3, s75, v207
	v_mul_f32_e32 v45, v205, v109
	v_lshlrev_b32_e32 v0, 1, v178
	v_lshl_add_u64 v[62:63], s[4:5], 0, v[0:1]
	v_fmamk_f32 v0, v2, 0x3c000000, v228
	v_cmp_gt_f32_e32 vcc, s58, v0
	v_mul_f32_e32 v2, 0x4f800000, v0
	s_nop 0
	v_cndmask_b32_e32 v0, v0, v2, vcc
	v_sqrt_f32_e32 v2, v0
	s_nop 0
	v_add_u32_e32 v64, -1, v2
	v_fma_f32 v65, -v64, v2, v0
	v_cmp_ge_f32_e64 s[36:37], 0, v65
	v_add_u32_e32 v65, 1, v2
	s_nop 0
	v_cndmask_b32_e64 v64, v2, v64, s[36:37]
	v_fma_f32 v2, -v65, v2, v0
	v_cmp_lt_f32_e64 s[36:37], 0, v2
	s_nop 1
	v_cndmask_b32_e64 v2, v64, v65, s[36:37]
	v_mul_f32_e32 v64, 0x37800000, v2
	v_cndmask_b32_e32 v2, v2, v64, vcc
	v_cmp_class_f32_e32 vcc, v0, v226
	s_nop 1
	v_cndmask_b32_e32 v0, v2, v0, vcc
	v_div_scale_f32 v2, s[4:5], v0, v0, 1.0
	v_rcp_f32_e32 v64, v2
	s_nop 0
	v_fma_f32 v65, -v2, v64, 1.0
	v_fmac_f32_e32 v64, v65, v64
	v_div_scale_f32 v65, vcc, 1.0, v0, 1.0
	v_mul_f32_e32 v66, v65, v64
	v_fma_f32 v67, -v2, v66, v65
	v_fmac_f32_e32 v66, v67, v64
	v_fma_f32 v2, -v2, v66, v65
	v_div_fmas_f32 v2, v2, v64, v66
	v_div_fixup_f32 v64, v2, v0, 1.0
	v_mul_u32_u24_e32 v0, 0xc00, v3
	v_lshl_add_u64 v[2:3], v[62:63], 0, v[0:1]
	v_mul_f32_e32 v0, v96, v64
	v_mul_f32_e32 v0, v0, v32
	v_cvt_pk_bf16_f32 v0, v0, s0
	global_store_short v[2:3], v0, off
	v_mul_f32_e32 v0, v97, v64
	v_mul_f32_e32 v0, v0, v30
	v_cvt_pk_bf16_f32 v0, v0, s0
	global_store_short v[2:3], v0, off offset:64
	v_mul_f32_e32 v0, v98, v64
	v_mul_f32_e32 v0, v0, v31
	v_cvt_pk_bf16_f32 v0, v0, s0
	global_store_short v[2:3], v0, off offset:128
	v_mul_f32_e32 v0, v99, v64
	v_mul_f32_e32 v0, v0, v45
	v_cvt_pk_bf16_f32 v0, v0, s0
	global_store_short v[2:3], v0, off offset:192
	v_fmamk_f32 v0, v61, 0x3c000000, v228
	v_cmp_gt_f32_e32 vcc, s58, v0
	v_mul_f32_e32 v61, 0x4f800000, v0
	s_nop 0
	v_cndmask_b32_e32 v0, v0, v61, vcc
	v_sqrt_f32_e32 v61, v0
	s_nop 0
	v_add_u32_e32 v62, -1, v61
	v_fma_f32 v63, -v62, v61, v0
	v_cmp_ge_f32_e64 s[36:37], 0, v63
	v_add_u32_e32 v63, 1, v61
	s_nop 0
	v_cndmask_b32_e64 v62, v61, v62, s[36:37]
	v_fma_f32 v61, -v63, v61, v0
	v_cmp_lt_f32_e64 s[36:37], 0, v61
	s_nop 1
	v_cndmask_b32_e64 v61, v62, v63, s[36:37]
	v_mul_f32_e32 v62, 0x37800000, v61
	v_cndmask_b32_e32 v61, v61, v62, vcc
	v_cmp_class_f32_e32 vcc, v0, v226
	s_nop 1
	v_cndmask_b32_e32 v0, v61, v0, vcc
	v_div_scale_f32 v61, s[4:5], v0, v0, 1.0
	v_rcp_f32_e32 v62, v61
	s_nop 0
	v_fma_f32 v63, -v61, v62, 1.0
	v_fmac_f32_e32 v62, v63, v62
	v_div_scale_f32 v63, vcc, 1.0, v0, 1.0
	v_mul_f32_e32 v64, v63, v62
	v_fma_f32 v65, -v61, v64, v63
	v_fmac_f32_e32 v64, v65, v62
	v_fma_f32 v61, -v61, v64, v63
	v_div_fmas_f32 v61, v61, v62, v64
	v_div_fixup_f32 v0, v61, v0, 1.0
	v_mul_f32_e32 v61, v94, v0
	v_mul_f32_e32 v61, v61, v32
	v_cvt_pk_bf16_f32 v61, v61, s0
	global_store_short v[2:3], v61, off offset:3072
	v_mul_f32_e32 v61, v91, v0
	v_mul_f32_e32 v61, v61, v30
	v_cvt_pk_bf16_f32 v61, v61, s0
	global_store_short v[2:3], v61, off offset:3136
	v_mul_f32_e32 v61, v92, v0
	v_mul_f32_e32 v0, v93, v0
	v_mul_f32_e32 v0, v0, v45
	v_cvt_pk_bf16_f32 v0, v0, s0
	global_store_short v[2:3], v0, off offset:3264
	v_fmamk_f32 v0, v60, 0x3c000000, v228
	v_cmp_gt_f32_e32 vcc, s58, v0
	v_mul_f32_e32 v60, 0x4f800000, v0
	v_mul_f32_e32 v61, v61, v31
	v_cndmask_b32_e32 v0, v0, v60, vcc
	v_sqrt_f32_e32 v60, v0
	v_cvt_pk_bf16_f32 v61, v61, s0
	global_store_short v[2:3], v61, off offset:3200
	v_add_u32_e32 v61, -1, v60
	v_fma_f32 v62, -v61, v60, v0
	v_cmp_ge_f32_e64 s[36:37], 0, v62
	v_add_u32_e32 v62, 1, v60
	s_nop 0
	v_cndmask_b32_e64 v61, v60, v61, s[36:37]
	v_fma_f32 v60, -v62, v60, v0
	v_cmp_lt_f32_e64 s[36:37], 0, v60
	s_nop 1
	v_cndmask_b32_e64 v60, v61, v62, s[36:37]
	v_mul_f32_e32 v61, 0x37800000, v60
	v_cndmask_b32_e32 v60, v60, v61, vcc
	v_cmp_class_f32_e32 vcc, v0, v226
	s_nop 1
	v_cndmask_b32_e32 v0, v60, v0, vcc
	v_div_scale_f32 v60, s[4:5], v0, v0, 1.0
	v_rcp_f32_e32 v61, v60
	s_nop 0
	v_fma_f32 v62, -v60, v61, 1.0
	v_fmac_f32_e32 v61, v62, v61
	v_div_scale_f32 v62, vcc, 1.0, v0, 1.0
	v_mul_f32_e32 v63, v62, v61
	v_fma_f32 v64, -v60, v63, v62
	v_fmac_f32_e32 v63, v64, v61
	v_fma_f32 v60, -v60, v63, v62
	v_div_fmas_f32 v60, v60, v61, v63
	v_div_fixup_f32 v0, v60, v0, 1.0
	v_mul_f32_e32 v60, v88, v0
	v_mul_f32_e32 v60, v60, v32
	v_cvt_pk_bf16_f32 v62, v60, s0
	v_add_co_u32_e32 v60, vcc, s57, v2
	s_nop 1
	v_addc_co_u32_e32 v61, vcc, 0, v3, vcc
	global_store_short v[60:61], v62, off offset:2048
	v_mul_f32_e32 v62, v89, v0
	v_mul_f32_e32 v62, v62, v30
	v_cvt_pk_bf16_f32 v62, v62, s0
	global_store_short v[60:61], v62, off offset:2112
	v_mul_f32_e32 v62, v90, v0
	v_mul_f32_e32 v0, v95, v0
	v_mul_f32_e32 v0, v0, v45
	v_cvt_pk_bf16_f32 v0, v0, s0
	global_store_short v[60:61], v0, off offset:2240
	v_fmamk_f32 v0, v59, 0x3c000000, v228
	v_cmp_gt_f32_e32 vcc, s58, v0
	v_mul_f32_e32 v59, 0x4f800000, v0
	v_mul_f32_e32 v62, v62, v31
	v_cndmask_b32_e32 v0, v0, v59, vcc
	v_sqrt_f32_e32 v59, v0
	v_cvt_pk_bf16_f32 v62, v62, s0
	global_store_short v[60:61], v62, off offset:2176
	v_add_u32_e32 v60, -1, v59
	v_fma_f32 v61, -v60, v59, v0
	v_cmp_ge_f32_e64 s[36:37], 0, v61
	v_add_u32_e32 v61, 1, v59
	s_nop 0
	v_cndmask_b32_e64 v60, v59, v60, s[36:37]
	v_fma_f32 v59, -v61, v59, v0
	v_cmp_lt_f32_e64 s[36:37], 0, v59
	s_nop 1
	v_cndmask_b32_e64 v59, v60, v61, s[36:37]
	v_mul_f32_e32 v60, 0x37800000, v59
	v_cndmask_b32_e32 v59, v59, v60, vcc
	v_cmp_class_f32_e32 vcc, v0, v226
	s_nop 1
	v_cndmask_b32_e32 v0, v59, v0, vcc
	v_div_scale_f32 v59, s[4:5], v0, v0, 1.0
	v_rcp_f32_e32 v60, v59
	s_nop 0
	v_fma_f32 v61, -v59, v60, 1.0
; __device__ __forceinline__ unsigned pk2(float lo, float hi) { return pg8::cvt_pk_bf16(lo, hi); }
; __device__ __forceinline__ int crow(int r, int hi) { return (r & 3) + 8 * (r >> 2) + 4 * hi; }
; template <int MODE> ...
;     ...
; #pragma unroll
;             for (int r = 0; r < 16; ++r) { const float inv = 1.0f / sqrtf(ss[r] * (1.f / 128.f) + 1e-5f); bf16* yp = Y + (tok0 + wq0 + crow(r, hi)) * 1536 + ycol + r32;
; #pragma unroll
;                 for (int c = 0; c < NC; ++c) yp[32 * c] = (bf16)(pk2(O[c][r] * inv * gsub[c], 0.f) & 0xffffu); }
	v_fmac_f32_e32 v60, v61, v60
	v_div_scale_f32 v61, vcc, 1.0, v0, 1.0
	v_mul_f32_e32 v62, v61, v60
	v_fma_f32 v63, -v59, v62, v61
	v_fmac_f32_e32 v62, v63, v60
	v_fma_f32 v59, -v59, v62, v61
	v_div_fmas_f32 v59, v59, v60, v62
	v_div_fixup_f32 v0, v59, v0, 1.0
	v_mul_f32_e32 v59, v87, v0
	v_mul_f32_e32 v59, v59, v32
	v_add_co_u32_e32 v60, vcc, s1, v2
	v_cvt_pk_bf16_f32 v59, v59, s0
	s_nop 0
	v_addc_co_u32_e32 v61, vcc, 0, v3, vcc
	global_store_short v[60:61], v59, off offset:1024
	v_mul_f32_e32 v59, v83, v0
	v_mul_f32_e32 v59, v59, v30
	v_cvt_pk_bf16_f32 v59, v59, s0
	global_store_short v[60:61], v59, off offset:1088
	v_mul_f32_e32 v59, v84, v0
	v_mul_f32_e32 v0, v85, v0
	v_mul_f32_e32 v0, v0, v45
	v_cvt_pk_bf16_f32 v0, v0, s0
	global_store_short v[60:61], v0, off offset:1216
	v_fmamk_f32 v0, v58, 0x3c000000, v228
	v_cmp_gt_f32_e32 vcc, s58, v0
	v_mul_f32_e32 v58, 0x4f800000, v0
	v_mul_f32_e32 v59, v59, v31
	v_cndmask_b32_e32 v0, v0, v58, vcc
	v_sqrt_f32_e32 v58, v0
	v_cvt_pk_bf16_f32 v59, v59, s0
	global_store_short v[60:61], v59, off offset:1152
	s_movk_i32 s1, 0x7000
	v_add_u32_e32 v59, -1, v58
	v_fma_f32 v60, -v59, v58, v0
	v_cmp_ge_f32_e64 s[36:37], 0, v60
	v_add_u32_e32 v60, 1, v58
	s_nop 0
	v_cndmask_b32_e64 v59, v58, v59, s[36:37]
	v_fma_f32 v58, -v60, v58, v0
	v_cmp_lt_f32_e64 s[36:37], 0, v58
	s_nop 1
	v_cndmask_b32_e64 v58, v59, v60, s[36:37]
	v_mul_f32_e32 v59, 0x37800000, v58
	v_cndmask_b32_e32 v58, v58, v59, vcc
	v_cmp_class_f32_e32 vcc, v0, v226
	s_nop 1
	v_cndmask_b32_e32 v0, v58, v0, vcc
	v_div_scale_f32 v58, s[4:5], v0, v0, 1.0
	v_rcp_f32_e32 v59, v58
	s_nop 0
	v_fma_f32 v60, -v58, v59, 1.0
	v_fmac_f32_e32 v59, v60, v59
	v_div_scale_f32 v60, vcc, 1.0, v0, 1.0
	v_mul_f32_e32 v61, v60, v59
	v_fma_f32 v62, -v58, v61, v60
	v_fmac_f32_e32 v61, v62, v59
	v_fma_f32 v58, -v58, v61, v60
	v_div_fmas_f32 v58, v58, v59, v61
	v_div_fixup_f32 v0, v58, v0, 1.0
	v_mul_f32_e32 v58, v80, v0
	v_mul_f32_e32 v58, v58, v32
	v_cvt_pk_bf16_f32 v60, v58, s0
	v_add_co_u32_e32 v58, vcc, s28, v2
	s_nop 1
	v_addc_co_u32_e32 v59, vcc, 0, v3, vcc
	global_store_short v[58:59], v60, off
	v_mul_f32_e32 v60, v81, v0
	v_mul_f32_e32 v60, v60, v30
	v_cvt_pk_bf16_f32 v60, v60, s0
	global_store_short v[58:59], v60, off offset:64
	v_mul_f32_e32 v60, v82, v0
	v_mul_f32_e32 v0, v86, v0
	v_mul_f32_e32 v0, v0, v45
	v_cvt_pk_bf16_f32 v0, v0, s0
	global_store_short v[58:59], v0, off offset:192
	v_fmamk_f32 v0, v57, 0x3c000000, v228
	v_cmp_gt_f32_e32 vcc, s58, v0
	v_mul_f32_e32 v57, 0x4f800000, v0
	v_mul_f32_e32 v60, v60, v31
	v_cndmask_b32_e32 v0, v0, v57, vcc
	v_sqrt_f32_e32 v57, v0
	v_cvt_pk_bf16_f32 v60, v60, s0
	global_store_short v[58:59], v60, off offset:128
	v_add_u32_e32 v60, -1, v57
	v_fma_f32 v61, -v60, v57, v0
	v_cmp_ge_f32_e64 s[36:37], 0, v61
	v_add_u32_e32 v61, 1, v57
	s_nop 0
	v_cndmask_b32_e64 v60, v57, v60, s[36:37]
	v_fma_f32 v57, -v61, v57, v0
	v_cmp_lt_f32_e64 s[36:37], 0, v57
	s_nop 1
	v_cndmask_b32_e64 v57, v60, v61, s[36:37]
	v_mul_f32_e32 v60, 0x37800000, v57
	v_cndmask_b32_e32 v57, v57, v60, vcc
	v_cmp_class_f32_e32 vcc, v0, v226
	s_nop 1
	v_cndmask_b32_e32 v0, v57, v0, vcc
	v_div_scale_f32 v57, s[4:5], v0, v0, 1.0
	v_rcp_f32_e32 v60, v57
	s_nop 0
	v_fma_f32 v61, -v57, v60, 1.0
	v_fmac_f32_e32 v60, v61, v60
	v_div_scale_f32 v61, vcc, 1.0, v0, 1.0
	v_mul_f32_e32 v62, v61, v60
	v_fma_f32 v63, -v57, v62, v61
	v_fmac_f32_e32 v62, v63, v60
	v_fma_f32 v57, -v57, v62, v61
	v_div_fmas_f32 v57, v57, v60, v62
	v_div_fixup_f32 v0, v57, v0, 1.0
	v_mul_f32_e32 v57, v79, v0
	v_mul_f32_e32 v57, v57, v32
	v_cvt_pk_bf16_f32 v57, v57, s0
	global_store_short v[58:59], v57, off offset:3072
	v_mul_f32_e32 v57, v74, v0
	v_mul_f32_e32 v57, v57, v30
	v_cvt_pk_bf16_f32 v57, v57, s0
	global_store_short v[58:59], v57, off offset:3136
	v_mul_f32_e32 v57, v78, v0
	v_mul_f32_e32 v0, v75, v0
	v_mul_f32_e32 v0, v0, v45
	v_cvt_pk_bf16_f32 v0, v0, s0
	global_store_short v[58:59], v0, off offset:3264
	v_fmamk_f32 v0, v49, 0x3c000000, v228
	v_cmp_gt_f32_e32 vcc, s58, v0
	v_mul_f32_e32 v49, 0x4f800000, v0
	v_mul_f32_e32 v57, v57, v31
	v_cndmask_b32_e32 v0, v0, v49, vcc
	v_sqrt_f32_e32 v49, v0
	v_cvt_pk_bf16_f32 v57, v57, s0
	global_store_short v[58:59], v57, off offset:3200
	v_add_u32_e32 v57, -1, v49
	v_fma_f32 v58, -v57, v49, v0
	v_cmp_ge_f32_e64 s[36:37], 0, v58
	v_add_u32_e32 v58, 1, v49
	s_nop 0
	v_cndmask_b32_e64 v57, v49, v57, s[36:37]
	v_fma_f32 v49, -v58, v49, v0
	v_cmp_lt_f32_e64 s[36:37], 0, v49
	s_nop 1
	v_cndmask_b32_e64 v49, v57, v58, s[36:37]
	v_mul_f32_e32 v57, 0x37800000, v49
	v_cndmask_b32_e32 v49, v49, v57, vcc
	v_cmp_class_f32_e32 vcc, v0, v226
	s_nop 1
	v_cndmask_b32_e32 v0, v49, v0, vcc
	v_div_scale_f32 v49, s[4:5], v0, v0, 1.0
	v_rcp_f32_e32 v57, v49
	s_nop 0
	v_fma_f32 v58, -v49, v57, 1.0
	v_fmac_f32_e32 v57, v58, v57
	v_div_scale_f32 v58, vcc, 1.0, v0, 1.0
	v_mul_f32_e32 v59, v58, v57
	v_fma_f32 v60, -v49, v59, v58
	v_fmac_f32_e32 v59, v60, v57
	v_fma_f32 v49, -v49, v59, v58
	v_div_fmas_f32 v49, v49, v57, v59
	v_div_fixup_f32 v0, v49, v0, 1.0
	v_mul_f32_e32 v49, v54, v0
	v_mul_f32_e32 v49, v49, v32
	v_add_co_u32_e32 v58, vcc, s1, v2
	v_cvt_pk_bf16_f32 v49, v49, s0
	s_nop 0
	v_addc_co_u32_e32 v59, vcc, 0, v3, vcc
	global_store_short v[58:59], v49, off offset:2048
	v_mul_f32_e32 v49, v55, v0
	v_mul_f32_e32 v49, v49, v30
	v_cvt_pk_bf16_f32 v49, v49, s0
	global_store_short v[58:59], v49, off offset:2112
	v_mul_f32_e32 v49, v56, v0
	v_mul_f32_e32 v0, v76, v0
	v_mul_f32_e32 v0, v0, v45
	v_cvt_pk_bf16_f32 v0, v0, s0
	global_store_short v[58:59], v0, off offset:2240
	v_fmamk_f32 v0, v48, 0x3c000000, v228
	v_cmp_gt_f32_e32 vcc, s58, v0
	v_mul_f32_e32 v48, 0x4f800000, v0
; __device__ __forceinline__ unsigned pk2(float lo, float hi) { return pg8::cvt_pk_bf16(lo, hi); }
; __device__ __forceinline__ int crow(int r, int hi) { return (r & 3) + 8 * (r >> 2) + 4 * hi; }
; template <int MODE> ...
;     ...
; #pragma unroll
;             for (int r = 0; r < 16; ++r) { const float inv = 1.0f / sqrtf(ss[r] * (1.f / 128.f) + 1e-5f); bf16* yp = Y + (tok0 + wq0 + crow(r, hi)) * 1536 + ycol + r32;
; #pragma unroll
;                 for (int c = 0; c < NC; ++c) yp[32 * c] = (bf16)(pk2(O[c][r] * inv * gsub[c], 0.f) & 0xffffu); }
	v_mul_f32_e32 v49, v49, v31
	v_cndmask_b32_e32 v0, v0, v48, vcc
	v_sqrt_f32_e32 v48, v0
	v_cvt_pk_bf16_f32 v49, v49, s0
	global_store_short v[58:59], v49, off offset:2176
	s_mov_b32 s1, 0x8000
	v_add_u32_e32 v49, -1, v48
	v_fma_f32 v54, -v49, v48, v0
	v_cmp_ge_f32_e64 s[36:37], 0, v54
	v_add_u32_e32 v54, 1, v48
	s_nop 0
	v_cndmask_b32_e64 v49, v48, v49, s[36:37]
	v_fma_f32 v48, -v54, v48, v0
	v_cmp_lt_f32_e64 s[36:37], 0, v48
	s_nop 1
	v_cndmask_b32_e64 v48, v49, v54, s[36:37]
	v_mul_f32_e32 v49, 0x37800000, v48
	v_cndmask_b32_e32 v48, v48, v49, vcc
	v_cmp_class_f32_e32 vcc, v0, v226
	s_nop 1
	v_cndmask_b32_e32 v0, v48, v0, vcc
	v_div_scale_f32 v48, s[4:5], v0, v0, 1.0
	v_rcp_f32_e32 v49, v48
	s_nop 0
	v_fma_f32 v54, -v48, v49, 1.0
	v_fmac_f32_e32 v49, v54, v49
	v_div_scale_f32 v54, vcc, 1.0, v0, 1.0
	v_mul_f32_e32 v55, v54, v49
	v_fma_f32 v56, -v48, v55, v54
	v_fmac_f32_e32 v55, v56, v49
	v_fma_f32 v48, -v48, v55, v54
	v_div_fmas_f32 v48, v48, v49, v55
	v_div_fixup_f32 v0, v48, v0, 1.0
	v_mul_f32_e32 v48, v53, v0
	v_mul_f32_e32 v48, v48, v32
	v_mul_f32_e32 v50, v50, v0
	v_cvt_pk_bf16_f32 v53, v48, s0
	v_add_co_u32_e32 v48, vcc, s1, v2
	v_mul_f32_e32 v50, v50, v30
	s_nop 0
	v_addc_co_u32_e32 v49, vcc, 0, v3, vcc
	v_cvt_pk_bf16_f32 v50, v50, s0
	global_store_short v[48:49], v50, off offset:1088
	v_mul_f32_e32 v50, v51, v0
	v_mul_f32_e32 v0, v52, v0
	v_mul_f32_e32 v0, v0, v45
	v_cvt_pk_bf16_f32 v0, v0, s0
	global_store_short v[48:49], v0, off offset:1216
	v_fmamk_f32 v0, v47, 0x3c000000, v228
	v_cmp_gt_f32_e32 vcc, s58, v0
	v_mul_f32_e32 v47, 0x4f800000, v0
	v_mul_f32_e32 v50, v50, v31
	v_cndmask_b32_e32 v0, v0, v47, vcc
	v_sqrt_f32_e32 v47, v0
	v_cvt_pk_bf16_f32 v50, v50, s0
	global_store_short v[48:49], v53, off offset:1024
	global_store_short v[48:49], v50, off offset:1152
	v_add_u32_e32 v48, -1, v47
	v_fma_f32 v49, -v48, v47, v0
	v_cmp_ge_f32_e64 s[36:37], 0, v49
	v_add_u32_e32 v49, 1, v47
	s_mov_b32 s1, 0xc000
	v_cndmask_b32_e64 v48, v47, v48, s[36:37]
	v_fma_f32 v47, -v49, v47, v0
	v_cmp_lt_f32_e64 s[36:37], 0, v47
	s_nop 1
	v_cndmask_b32_e64 v47, v48, v49, s[36:37]
	v_mul_f32_e32 v48, 0x37800000, v47
	v_cndmask_b32_e32 v47, v47, v48, vcc
	v_cmp_class_f32_e32 vcc, v0, v226
	s_nop 1
	v_cndmask_b32_e32 v0, v47, v0, vcc
	v_div_scale_f32 v47, s[4:5], v0, v0, 1.0
	v_rcp_f32_e32 v48, v47
	s_nop 0
	v_fma_f32 v49, -v47, v48, 1.0
	v_fmac_f32_e32 v48, v49, v48
	v_div_scale_f32 v49, vcc, 1.0, v0, 1.0
	v_mul_f32_e32 v50, v49, v48
	v_fma_f32 v51, -v47, v50, v49
	v_fmac_f32_e32 v50, v51, v48
	v_fma_f32 v47, -v47, v50, v49
	v_div_fmas_f32 v47, v47, v48, v50
	v_div_fixup_f32 v0, v47, v0, 1.0
	v_mul_f32_e32 v39, v39, v0
	v_mul_f32_e32 v39, v39, v32
	v_add_co_u32_e32 v48, vcc, s1, v2
	v_cvt_pk_bf16_f32 v39, v39, s0
	s_nop 0
	v_addc_co_u32_e32 v49, vcc, 0, v3, vcc
	global_store_short v[48:49], v39, off
	v_mul_f32_e32 v39, v40, v0
	v_mul_f32_e32 v39, v39, v30
	v_cvt_pk_bf16_f32 v39, v39, s0
	global_store_short v[48:49], v39, off offset:64
	v_mul_f32_e32 v39, v41, v0
	v_mul_f32_e32 v0, v42, v0
	v_mul_f32_e32 v0, v0, v45
	v_mul_f32_e32 v39, v39, v31
	v_cvt_pk_bf16_f32 v0, v0, s0
	v_cvt_pk_bf16_f32 v39, v39, s0
	global_store_short v[48:49], v0, off offset:192
	v_fmamk_f32 v0, v46, 0x3c000000, v228
	global_store_short v[48:49], v39, off offset:128
	v_cmp_gt_f32_e32 vcc, s58, v0
	v_mul_f32_e32 v39, 0x4f800000, v0
	s_mov_b32 s1, 0xd000
	v_cndmask_b32_e32 v0, v0, v39, vcc
	v_sqrt_f32_e32 v39, v0
	s_nop 0
	v_add_u32_e32 v40, -1, v39
	v_fma_f32 v41, -v40, v39, v0
	v_cmp_ge_f32_e64 s[36:37], 0, v41
	v_add_u32_e32 v41, 1, v39
	s_nop 0
	v_cndmask_b32_e64 v40, v39, v40, s[36:37]
	v_fma_f32 v39, -v41, v39, v0
	v_cmp_lt_f32_e64 s[36:37], 0, v39
	s_nop 1
	v_cndmask_b32_e64 v39, v40, v41, s[36:37]
	v_mul_f32_e32 v40, 0x37800000, v39
	v_cndmask_b32_e32 v39, v39, v40, vcc
	v_cmp_class_f32_e32 vcc, v0, v226
	s_nop 1
	v_cndmask_b32_e32 v0, v39, v0, vcc
	v_div_scale_f32 v39, s[4:5], v0, v0, 1.0
	v_rcp_f32_e32 v40, v39
	s_nop 0
	v_fma_f32 v41, -v39, v40, 1.0
	v_fmac_f32_e32 v40, v41, v40
	v_div_scale_f32 v41, vcc, 1.0, v0, 1.0
	v_mul_f32_e32 v42, v41, v40
	v_fma_f32 v46, -v39, v42, v41
	v_fmac_f32_e32 v42, v46, v40
	v_fma_f32 v39, -v39, v42, v41
	v_div_fmas_f32 v39, v39, v40, v42
	v_div_fixup_f32 v0, v39, v0, 1.0
	v_mul_f32_e32 v34, v34, v0
	v_mul_f32_e32 v34, v34, v30
	v_cvt_pk_bf16_f32 v34, v34, s0
	v_mul_f32_e32 v37, v37, v0
	global_store_short v[48:49], v34, off offset:3136
	v_mul_f32_e32 v34, v35, v0
	v_mul_f32_e32 v0, v36, v0
	v_mul_f32_e32 v0, v0, v45
	v_mul_f32_e32 v34, v34, v31
	v_cvt_pk_bf16_f32 v0, v0, s0
	v_cvt_pk_bf16_f32 v34, v34, s0
	global_store_short v[48:49], v0, off offset:3264
	v_fmamk_f32 v0, v44, 0x3c000000, v228
	global_store_short v[48:49], v34, off offset:3200
	v_cmp_gt_f32_e32 vcc, s58, v0
	v_mul_f32_e32 v34, 0x4f800000, v0
	v_mul_f32_e32 v37, v37, v32
	v_cndmask_b32_e32 v0, v0, v34, vcc
	v_sqrt_f32_e32 v34, v0
	v_cvt_pk_bf16_f32 v37, v37, s0
	global_store_short v[48:49], v37, off offset:3072
	v_add_u32_e32 v35, -1, v34
	v_fma_f32 v36, -v35, v34, v0
	v_cmp_ge_f32_e64 s[36:37], 0, v36
	v_add_u32_e32 v36, 1, v34
	s_nop 0
	v_cndmask_b32_e64 v35, v34, v35, s[36:37]
	v_fma_f32 v34, -v36, v34, v0
	v_cmp_lt_f32_e64 s[36:37], 0, v34
	s_nop 1
	v_cndmask_b32_e64 v34, v35, v36, s[36:37]
	v_mul_f32_e32 v35, 0x37800000, v34
	v_cndmask_b32_e32 v34, v34, v35, vcc
	v_cmp_class_f32_e32 vcc, v0, v226
	s_nop 1
	v_cndmask_b32_e32 v0, v34, v0, vcc
	v_div_scale_f32 v34, s[4:5], v0, v0, 1.0
	v_rcp_f32_e32 v35, v34
	s_nop 0
	v_fma_f32 v36, -v34, v35, 1.0
	v_fmac_f32_e32 v35, v36, v35
	v_div_scale_f32 v36, vcc, 1.0, v0, 1.0
	v_mul_f32_e32 v37, v36, v35
	v_fma_f32 v39, -v34, v37, v36
; __device__ __forceinline__ unsigned pk2(float lo, float hi) { return pg8::cvt_pk_bf16(lo, hi); }
; __device__ __forceinline__ int crow(int r, int hi) { return (r & 3) + 8 * (r >> 2) + 4 * hi; }
; template <int MODE> ...
;     ...
; #pragma unroll
;             for (int r = 0; r < 16; ++r) { const float inv = 1.0f / sqrtf(ss[r] * (1.f / 128.f) + 1e-5f); bf16* yp = Y + (tok0 + wq0 + crow(r, hi)) * 1536 + ycol + r32;
; #pragma unroll
;                 for (int c = 0; c < NC; ++c) yp[32 * c] = (bf16)(pk2(O[c][r] * inv * gsub[c], 0.f) & 0xffffu); }
	v_fmac_f32_e32 v37, v39, v35
	v_fma_f32 v34, -v34, v37, v36
	v_div_fmas_f32 v34, v34, v35, v37
	v_div_fixup_f32 v0, v34, v0, 1.0
	v_mul_f32_e32 v26, v26, v0
	v_mul_f32_e32 v26, v32, v26
	v_add_co_u32_e32 v34, vcc, s1, v2
	v_cvt_pk_bf16_f32 v26, v26, s0
	s_nop 0
	v_addc_co_u32_e32 v35, vcc, 0, v3, vcc
	global_store_short v[34:35], v26, off offset:2048
	v_mul_f32_e32 v26, v27, v0
	v_mul_f32_e32 v26, v26, v30
	v_cvt_pk_bf16_f32 v26, v26, s0
	global_store_short v[34:35], v26, off offset:2112
	v_mul_f32_e32 v26, v28, v0
	v_mul_f32_e32 v0, v38, v0
	v_mul_f32_e32 v0, v0, v45
	v_mul_f32_e32 v26, v26, v31
	v_cvt_pk_bf16_f32 v0, v0, s0
	v_cvt_pk_bf16_f32 v26, v26, s0
	global_store_short v[34:35], v0, off offset:2240
	v_fmamk_f32 v0, v43, 0x3c000000, v228
	global_store_short v[34:35], v26, off offset:2176
	v_cmp_gt_f32_e32 vcc, s58, v0
	v_mul_f32_e32 v26, 0x4f800000, v0
	s_mov_b32 s1, 0xe000
	v_cndmask_b32_e32 v0, v0, v26, vcc
	v_sqrt_f32_e32 v26, v0
	s_nop 0
	v_add_u32_e32 v27, -1, v26
	v_fma_f32 v28, -v27, v26, v0
	v_cmp_ge_f32_e64 s[36:37], 0, v28
	v_add_u32_e32 v28, 1, v26
	s_nop 0
	v_cndmask_b32_e64 v27, v26, v27, s[36:37]
	v_fma_f32 v26, -v28, v26, v0
	v_cmp_lt_f32_e64 s[36:37], 0, v26
	s_nop 1
	v_cndmask_b32_e64 v26, v27, v28, s[36:37]
	v_mul_f32_e32 v27, 0x37800000, v26
	v_cndmask_b32_e32 v26, v26, v27, vcc
	v_cmp_class_f32_e32 vcc, v0, v226
	s_nop 1
	v_cndmask_b32_e32 v0, v26, v0, vcc
	v_div_scale_f32 v26, s[4:5], v0, v0, 1.0
	v_rcp_f32_e32 v27, v26
	s_nop 0
	v_fma_f32 v28, -v26, v27, 1.0
	v_fmac_f32_e32 v27, v28, v27
	v_div_scale_f32 v28, vcc, 1.0, v0, 1.0
	v_mul_f32_e32 v34, v28, v27
	v_fma_f32 v35, -v26, v34, v28
	v_fmac_f32_e32 v34, v35, v27
	v_fma_f32 v26, -v26, v34, v28
	v_div_fmas_f32 v26, v26, v27, v34
	v_div_fixup_f32 v0, v26, v0, 1.0
	v_mul_f32_e32 v21, v21, v0
	v_add_co_u32_e32 v26, vcc, s1, v2
	v_mul_f32_e32 v21, v30, v21
	s_nop 0
	v_addc_co_u32_e32 v27, vcc, 0, v3, vcc
	v_cvt_pk_bf16_f32 v21, v21, s0
	v_mul_f32_e32 v25, v25, v0
	global_store_short v[26:27], v21, off offset:1088
	v_mul_f32_e32 v21, v22, v0
	v_mul_f32_e32 v0, v23, v0
	v_mul_f32_e32 v0, v0, v45
	v_mul_f32_e32 v21, v21, v31
	v_cvt_pk_bf16_f32 v0, v0, s0
	v_cvt_pk_bf16_f32 v21, v21, s0
	global_store_short v[26:27], v0, off offset:1216
	v_fmamk_f32 v0, v33, 0x3c000000, v228
	global_store_short v[26:27], v21, off offset:1152
	v_cmp_gt_f32_e32 vcc, s58, v0
	v_mul_f32_e32 v21, 0x4f800000, v0
	v_mul_f32_e32 v25, v32, v25
	v_cndmask_b32_e32 v0, v0, v21, vcc
	v_sqrt_f32_e32 v21, v0
	v_cvt_pk_bf16_f32 v25, v25, s0
	global_store_short v[26:27], v25, off offset:1024
	s_mov_b32 s1, 0x12000
	v_add_u32_e32 v22, -1, v21
	v_fma_f32 v23, -v22, v21, v0
	v_cmp_ge_f32_e64 s[36:37], 0, v23
	v_add_u32_e32 v23, 1, v21
	s_nop 0
	v_cndmask_b32_e64 v22, v21, v22, s[36:37]
	v_fma_f32 v21, -v23, v21, v0
	v_cmp_lt_f32_e64 s[36:37], 0, v21
	s_nop 1
	v_cndmask_b32_e64 v21, v22, v23, s[36:37]
	v_mul_f32_e32 v22, 0x37800000, v21
	v_cndmask_b32_e32 v21, v21, v22, vcc
	v_cmp_class_f32_e32 vcc, v0, v226
	s_nop 1
	v_cndmask_b32_e32 v0, v21, v0, vcc
	v_div_scale_f32 v21, s[4:5], v0, v0, 1.0
	v_rcp_f32_e32 v22, v21
	s_nop 0
	v_fma_f32 v23, -v21, v22, 1.0
	v_fmac_f32_e32 v22, v23, v22
	v_div_scale_f32 v23, vcc, 1.0, v0, 1.0
	v_mul_f32_e32 v25, v23, v22
	v_fma_f32 v26, -v21, v25, v23
	v_fmac_f32_e32 v25, v26, v22
	v_fma_f32 v21, -v21, v25, v23
	v_div_fmas_f32 v21, v21, v22, v25
	v_div_fixup_f32 v0, v21, v0, 1.0
	v_mul_f32_e32 v18, v18, v0
	v_mul_f32_e32 v18, v32, v18
	v_add_co_u32_e32 v22, vcc, s1, v2
	v_cvt_pk_bf16_f32 v18, v18, s0
	s_nop 0
	v_addc_co_u32_e32 v23, vcc, 0, v3, vcc
	global_store_short v[22:23], v18, off
	v_mul_f32_e32 v18, v19, v0
	v_mul_f32_e32 v18, v30, v18
	v_cvt_pk_bf16_f32 v18, v18, s0
	global_store_short v[22:23], v18, off offset:64
	v_mul_f32_e32 v18, v20, v0
	v_mul_f32_e32 v0, v24, v0
	v_mul_f32_e32 v0, v0, v45
	v_mul_f32_e32 v18, v31, v18
	v_cvt_pk_bf16_f32 v0, v0, s0
	v_cvt_pk_bf16_f32 v18, v18, s0
	global_store_short v[22:23], v0, off offset:192
	v_fmamk_f32 v0, v29, 0x3c000000, v228
	global_store_short v[22:23], v18, off offset:128
	v_cmp_gt_f32_e32 vcc, s58, v0
	v_mul_f32_e32 v18, 0x4f800000, v0
	s_mov_b32 s1, 0x13000
	v_cndmask_b32_e32 v0, v0, v18, vcc
	v_sqrt_f32_e32 v18, v0
	s_nop 0
	v_add_u32_e32 v19, -1, v18
	v_fma_f32 v20, -v19, v18, v0
	v_cmp_ge_f32_e64 s[36:37], 0, v20
	v_add_u32_e32 v20, 1, v18
	s_nop 0
; __device__ __forceinline__ unsigned pk2(float lo, float hi) { return pg8::cvt_pk_bf16(lo, hi); }
; __device__ __forceinline__ int crow(int r, int hi) { return (r & 3) + 8 * (r >> 2) + 4 * hi; }
; template <int MODE> ...
;     ...
;             for (int r = 0; r < 16; ++r) { const float inv = 1.0f / sqrtf(ss[r] * (1.f / 128.f) + 1e-5f); bf16* yp = Y + (tok0 + wq0 + crow(r, hi)) * 1536 + ycol + r32;
; #pragma unroll
;                 for (int c = 0; c < NC; ++c) yp[32 * c] = (bf16)(pk2(O[c][r] * inv * gsub[c], 0.f) & 0xffffu); }
	v_cndmask_b32_e64 v19, v18, v19, s[36:37]
	v_fma_f32 v18, -v20, v18, v0
	v_cmp_lt_f32_e64 s[36:37], 0, v18
	s_nop 1
	v_cndmask_b32_e64 v18, v19, v20, s[36:37]
	v_mul_f32_e32 v19, 0x37800000, v18
	v_cndmask_b32_e32 v18, v18, v19, vcc
	v_cmp_class_f32_e32 vcc, v0, v226
	s_nop 1
	v_cndmask_b32_e32 v0, v18, v0, vcc
	v_div_scale_f32 v18, s[4:5], v0, v0, 1.0
	v_rcp_f32_e32 v19, v18
	s_nop 0
	v_fma_f32 v20, -v18, v19, 1.0
	v_fmac_f32_e32 v19, v20, v19
	v_div_scale_f32 v20, vcc, 1.0, v0, 1.0
	v_mul_f32_e32 v21, v20, v19
	v_fma_f32 v24, -v18, v21, v20
	v_fmac_f32_e32 v21, v24, v19
	v_fma_f32 v18, -v18, v21, v20
	v_div_fmas_f32 v18, v18, v19, v21
	v_div_fixup_f32 v0, v18, v0, 1.0
	v_mul_f32_e32 v11, v11, v0
	v_mul_f32_e32 v11, v30, v11
	v_cvt_pk_bf16_f32 v11, v11, s0
	v_mul_f32_e32 v14, v14, v0
	global_store_short v[22:23], v11, off offset:3136
	v_mul_f32_e32 v11, v12, v0
	v_mul_f32_e32 v0, v13, v0
	v_mul_f32_e32 v0, v45, v0
	v_mul_f32_e32 v11, v31, v11
	v_cvt_pk_bf16_f32 v0, v0, s0
	v_cvt_pk_bf16_f32 v11, v11, s0
	global_store_short v[22:23], v0, off offset:3264
	v_fmamk_f32 v0, v17, 0x3c000000, v228
	global_store_short v[22:23], v11, off offset:3200
	v_cmp_gt_f32_e32 vcc, s58, v0
	v_mul_f32_e32 v11, 0x4f800000, v0
	v_mul_f32_e32 v14, v32, v14
	v_cndmask_b32_e32 v0, v0, v11, vcc
	v_sqrt_f32_e32 v11, v0
	v_cvt_pk_bf16_f32 v14, v14, s0
	global_store_short v[22:23], v14, off offset:3072
	v_add_u32_e32 v12, -1, v11
	v_fma_f32 v13, -v12, v11, v0
	v_cmp_ge_f32_e64 s[36:37], 0, v13
	v_add_u32_e32 v13, 1, v11
	s_nop 0
	v_cndmask_b32_e64 v12, v11, v12, s[36:37]
	v_fma_f32 v11, -v13, v11, v0
	v_cmp_lt_f32_e64 s[36:37], 0, v11
	s_nop 1
	v_cndmask_b32_e64 v11, v12, v13, s[36:37]
	v_mul_f32_e32 v12, 0x37800000, v11
	v_cndmask_b32_e32 v11, v11, v12, vcc
	v_cmp_class_f32_e32 vcc, v0, v226
	s_nop 1
	v_cndmask_b32_e32 v0, v11, v0, vcc
	v_div_scale_f32 v11, s[4:5], v0, v0, 1.0
	v_rcp_f32_e32 v12, v11
	s_nop 0
	v_fma_f32 v13, -v11, v12, 1.0
	v_fmac_f32_e32 v12, v13, v12
	v_div_scale_f32 v13, vcc, 1.0, v0, 1.0
	v_mul_f32_e32 v14, v13, v12
	v_fma_f32 v17, -v11, v14, v13
	v_fmac_f32_e32 v14, v17, v12
	v_fma_f32 v11, -v11, v14, v13
	v_div_fmas_f32 v11, v11, v12, v14
	v_div_fixup_f32 v0, v11, v0, 1.0
	v_mul_f32_e32 v8, v8, v0
	v_mul_f32_e32 v8, v32, v8
	v_add_co_u32_e32 v12, vcc, s1, v2
	v_cvt_pk_bf16_f32 v8, v8, s0
	s_nop 0
	v_addc_co_u32_e32 v13, vcc, 0, v3, vcc
	global_store_short v[12:13], v8, off offset:2048
	v_mul_f32_e32 v8, v9, v0
	v_mul_f32_e32 v8, v30, v8
	v_cvt_pk_bf16_f32 v8, v8, s0
	global_store_short v[12:13], v8, off offset:2112
	v_mul_f32_e32 v8, v10, v0
	v_mul_f32_e32 v0, v15, v0
	v_mul_f32_e32 v0, v45, v0
	v_mul_f32_e32 v8, v31, v8
	v_cvt_pk_bf16_f32 v0, v0, s0
	v_cvt_pk_bf16_f32 v8, v8, s0
	global_store_short v[12:13], v0, off offset:2240
	v_fmamk_f32 v0, v16, 0x3c000000, v228
	global_store_short v[12:13], v8, off offset:2176
	v_cmp_gt_f32_e32 vcc, s58, v0
	v_mul_f32_e32 v8, 0x4f800000, v0
	s_nop 0
	v_cndmask_b32_e32 v0, v0, v8, vcc
	v_sqrt_f32_e32 v8, v0
	s_nop 0
	v_add_u32_e32 v9, -1, v8
	v_fma_f32 v10, -v9, v8, v0
	v_cmp_ge_f32_e64 s[36:37], 0, v10
	v_add_u32_e32 v10, 1, v8
	s_nop 0
	v_cndmask_b32_e64 v9, v8, v9, s[36:37]
	v_fma_f32 v8, -v10, v8, v0
	v_cmp_lt_f32_e64 s[36:37], 0, v8
	s_nop 1
	v_cndmask_b32_e64 v8, v9, v10, s[36:37]
	v_mul_f32_e32 v9, 0x37800000, v8
	v_cndmask_b32_e32 v8, v8, v9, vcc
	v_cmp_class_f32_e32 vcc, v0, v226
	s_nop 1
	v_cndmask_b32_e32 v0, v8, v0, vcc
	v_div_scale_f32 v8, s[4:5], v0, v0, 1.0
	v_rcp_f32_e32 v9, v8
	s_nop 0
	v_fma_f32 v10, -v8, v9, 1.0
	v_fmac_f32_e32 v9, v10, v9
	v_div_scale_f32 v10, vcc, 1.0, v0, 1.0
	v_mul_f32_e32 v11, v10, v9
	v_fma_f32 v12, -v8, v11, v10
	v_fmac_f32_e32 v11, v12, v9
	v_fma_f32 v8, -v8, v11, v10
	v_div_fmas_f32 v8, v8, v9, v11
	v_div_fixup_f32 v0, v8, v0, 1.0
	v_mul_f32_e32 v4, v4, v0
	v_add_co_u32_e32 v2, vcc, 0x14000, v2
	v_mul_f32_e32 v4, v30, v4
	s_nop 0
	v_addc_co_u32_e32 v3, vcc, 0, v3, vcc
	v_cvt_pk_bf16_f32 v4, v4, s0
	v_mul_f32_e32 v7, v7, v0
	global_store_short v[2:3], v4, off offset:1088
	v_mul_f32_e32 v4, v5, v0
	v_mul_f32_e32 v0, v6, v0
	v_mul_f32_e32 v7, v32, v7
	v_mul_f32_e32 v4, v31, v4
	v_mul_f32_e32 v0, v45, v0
	v_cvt_pk_bf16_f32 v7, v7, s0
	v_cvt_pk_bf16_f32 v4, v4, s0
	v_cvt_pk_bf16_f32 v0, v0, s0
	global_store_short v[2:3], v7, off offset:1024
	global_store_short v[2:3], v4, off offset:1152
	global_store_short v[2:3], v0, off offset:1216
